# grid barrier: acquire invalidate moved to wave 1 right after arrival, off thread 0 chain
# speedup vs baseline: 1.0494x; 1.0012x over previous
.LBB0_505:
	v_readlane_b32 s2, v252, 11
	v_readlane_b32 s3, v252, 12
	s_mov_b64 s[0:1], -1
	s_and_b64 vcc, exec, s[2:3]
	s_cbranch_vccz .LBB0_559
	s_waitcnt vmcnt(0)
	s_waitcnt vmcnt(0) lgkmcnt(0)
	s_barrier
	v_readfirstlane_b32 s2, v160
	s_cmp_eq_u32 s2, 64
	s_cbranch_scc0 .Lxb_noinv
	buffer_inv sc1
.Lxb_noinv:
	s_mov_b64 s[0:1], exec
	v_readlane_b32 s2, v250, 3
	v_readlane_b32 s3, v250, 4
	s_and_b64 s[2:3], s[0:1], s[2:3]
	s_mov_b64 exec, s[2:3]
	s_cbranch_execz .LBB0_558
	s_add_i32 s28, 0, 0x20000
	v_mov_b32_e32 v0, s28
	s_waitcnt vmcnt(0) expcnt(0) lgkmcnt(0)
	ds_read_b32 v3, v0
	v_readlane_b32 s2, v254, 50
	s_waitcnt lgkmcnt(0)
	v_cmp_ne_u32_e32 vcc, 0, v3
	v_mov_b32_e32 v0, s2
	ds_read_b32 v2, v0
	s_cbranch_vccnz .LBB0_522
	s_mov_b32 s29, 1
	s_branch .LBB0_510

.Lxb_poll:
	v_readlane_b32 s20, v253, 17
	v_readlane_b32 s21, v253, 18
	s_waitcnt lgkmcnt(0)
	s_nop 3
	v_add_u32_e32 v7, 1, v0
	v_mul_lo_u32 v7, v7, v2
	global_load_dword v2, v1, s[20:21] sc1
	s_waitcnt vmcnt(0)
	v_sub_u32_e32 v2, v2, v7
	v_cmp_gt_i32_e32 vcc, 0, v2
	s_and_saveexec_b64 s[20:21], vcc
	s_cbranch_execz .LBB0_537
	s_mov_b32 s35, 1
	s_mov_b64 s[22:23], 0
	s_branch .LBB0_528

.LBB0_558:
	s_or_b64 exec, exec, s[0:1]
	s_mov_b64 s[0:1], 0
	s_waitcnt vmcnt(0) lgkmcnt(0)
	s_barrier
